# chain tasks: the acquire is issued before polling the level-1 completion counter
# baseline (speedup 1.0000x reference)
.LBB0_618:
	v_readlane_b32 s0, v254, 46
	s_lshr_b32 s1, s0, 1
	s_mov_b64 s[2:3], exec
	v_readlane_b32 s4, v254, 6
	v_readlane_b32 s5, v254, 7
	s_and_b64 s[4:5], s[2:3], s[4:5]
	v_readlane_b32 s64, v254, 26
	v_readlane_b32 s54, v254, 54
	v_readlane_b32 s9, v254, 44
	s_mov_b64 exec, s[4:5]
	s_cbranch_execz .LBB0_645
	s_lshl_b32 s0, s1, 8
	s_add_u32 s0, s82, s0
	s_addc_u32 s5, s83, 0
	s_add_u32 s4, s0, 0x18000
	s_addc_u32 s5, s5, 0
	s_mov_b32 s0, 0x400001
	v_mov_b32_e32 v2, 0
	buffer_inv sc1
	s_branch .LBB0_621

.LBB0_643:
	s_cmp_lt_u32 s22, 0x40001
	s_mov_b64 s[18:19], 0
	s_cselect_b64 s[20:21], -1, 0
	s_and_b64 vcc, exec, s[20:21]
	s_cbranch_vccz .LBB0_637
	s_branch .LBB0_642
.LBB0_644:
	s_waitcnt vmcnt(0)
.LBB0_645:
	s_or_b64 exec, exec, s[2:3]
	s_lshl_b32 s0, s64, 1
	s_and_b32 s0, s0, 2
	v_readlane_b32 s2, v254, 48
	s_add_i32 s0, s0, s2
	s_lshl_b32 s1, s1, 4
	v_readlane_b32 s2, v254, 27
	s_mov_b32 s4, 0
	v_lshlrev_b32_e32 v34, 4, v183
	s_cmp_lt_i32 s2, 4
	s_mov_b64 s[2:3], -1
	s_barrier
	s_cbranch_scc0 .LBB0_649
	v_readlane_b32 s3, v254, 27
	s_lshl_b32 s8, s3, 11
	s_add_i32 s3, 0, 0x14000
	s_add_i32 s5, s3, s8
	v_add_u32_e32 v35, s5, v34
	s_mov_b32 s5, s4
	v_add_u32_e32 v40, s3, v34
	s_lshl_b32 s3, s0, 13
	s_mov_b32 s6, s4
	s_mov_b32 s7, s4
	v_mov_b64_e32 v[4:5], s[4:5]
	s_add_i32 s3, s8, s3
	s_lshl_b32 s2, s1, 15
	v_mov_b64_e32 v[6:7], s[6:7]
	s_ashr_i32 s5, s3, 31
	s_add_u32 s3, s82, s3
	v_add_u32_e32 v2, s8, v40
	s_addc_u32 s5, s83, s5
	ds_write_b128 v35, v[4:7]
	ds_write_b128 v2, v[4:7] offset:1024
	s_add_u32 s2, s3, s2
	v_lshlrev_b32_e32 v36, 5, v183
	s_waitcnt lgkmcnt(0)
	v_mov_b32_e32 v37, 0
	s_addc_u32 s3, s5, 0
	v_lshl_add_u64 v[2:3], s[2:3], 0, v[36:37]
	s_mov_b64 s[2:3], 0xfc08000
	v_lshl_add_u64 v[38:39], v[2:3], 0, s[2:3]
	s_movk_i32 s5, 0x2000
	s_mov_b64 s[2:3], 0x8000
